# v44 with NO decode waves beside the running recurrence
# baseline (speedup 1.0000x reference)
; __device__ __forceinline__ void p3_scan_and_sb(const Params& P, float* lds) {
;     ...
;         if (wave >= 5 + SC_FREE_WAVES) {
;             constexpr unsigned NCHU = SEQ / SCH;
;             while (scw[1] < NCHU || scw[2] < NCHU || scw[3] < NCHU || scw[4] < NCHU) __builtin_amdgcn_s_sleep(32);
;         }
.LBB0_1246:
	s_waitcnt vmcnt(0)
	s_and_saveexec_b64 s[0:1], s[4:5]
	s_add_i32 s2, 0, 0x23000
	v_mov_b32_e32 v2, 0x100
	v_mov_b32_e32 v3, s2
	ds_write_b32 v3, v2
	s_or_b64 exec, exec, s[0:1]
	s_movk_i32 s0, 0x13f
	v_cmp_lt_u32_e32 vcc, s0, v0
	s_and_saveexec_b64 s[0:1], vcc
	s_cbranch_execz .LBB0_1260
	s_branch .LBB0_1252

; __device__ __forceinline__ void p3_scan_and_sb(const Params& P, float* lds) {
;     ...
;         if (wave >= 5 + SC_FREE_WAVES) {
;             constexpr unsigned NCHU = SEQ / SCH;
;             while (scw[1] < NCHU || scw[2] < NCHU || scw[3] < NCHU || scw[4] < NCHU) __builtin_amdgcn_s_sleep(32);
;         }
.LBB0_1251:
	s_movk_i32 s0, 0x13f
	v_cmp_lt_u32_e32 vcc, s0, v0
	s_and_saveexec_b64 s[0:1], vcc
	s_cbranch_execz .LBB0_1260
